# residual-add bf16 GEMM epilogue: residual loads batched per 4 row groups instead of one round trip per 16x8 piece
# speedup vs baseline: 1.0353x; 1.0005x over previous
.LBB0_2005:
	s_lshl_b32 s11, s0, 8
	s_mov_b64 s[72:73], -1
	s_mov_b64 s[2:3], 0
	s_cmp_lt_i32 s41, 3
	s_mov_b64 s[24:25], 0
	s_cbranch_scc1 .LBB0_2013
	s_cmp_gt_i32 s41, 3
	s_cbranch_scc0 .LBB0_2010
	s_cmp_eq_u32 s41, 4
	s_mov_b64 s[24:25], -1
	s_cbranch_scc0 .LBB0_2009
	v_lshl_or_b32 v130, s1, 8, v164
	v_add_u32_e32 v132, s11, v161
	v_ashrrev_i32_e32 v131, 31, v130
	s_waitcnt lgkmcnt(0)
	v_mad_i64_i32 v[134:135], s[24:25], s30, v132, v[130:131]
	v_lshl_add_u64 v[200:201], v[134:135], 2, s[94:95]
	v_lshl_add_u64 v[134:135], v[134:135], 1, s[34:35]
	global_load_dwordx4 v[168:171], v[200:201], off offset:16
	global_load_dwordx4 v[172:175], v[200:201], off
	global_load_dwordx4 v[176:179], v[200:201], off offset:528
	global_load_dwordx4 v[180:183], v[200:201], off offset:512
	v_add_u32_e32 v133, 0x10, v132
	v_mad_i64_i32 v[136:137], s[24:25], s30, v133, v[130:131]
	v_lshl_add_u64 v[200:201], v[136:137], 2, s[94:95]
	v_lshl_add_u64 v[136:137], v[136:137], 1, s[34:35]
	global_load_dwordx4 v[184:187], v[200:201], off offset:16
	global_load_dwordx4 v[188:191], v[200:201], off
	global_load_dwordx4 v[192:195], v[200:201], off offset:528
	global_load_dwordx4 v[196:199], v[200:201], off offset:512
	v_add_u32_e32 v133, 0x20, v132
	v_mad_i64_i32 v[154:155], s[24:25], s30, v133, v[130:131]
	v_lshl_add_u64 v[200:201], v[154:155], 2, s[94:95]
	v_lshl_add_u64 v[154:155], v[154:155], 1, s[34:35]
	global_load_dwordx4 v[220:223], v[200:201], off offset:16
	global_load_dwordx4 v[224:227], v[200:201], off
	global_load_dwordx4 v[228:231], v[200:201], off offset:528
	global_load_dwordx4 v[232:235], v[200:201], off offset:512
	v_add_u32_e32 v133, 0x30, v132
	v_mad_i64_i32 v[156:157], s[24:25], s30, v133, v[130:131]
	v_lshl_add_u64 v[200:201], v[156:157], 2, s[94:95]
	v_lshl_add_u64 v[156:157], v[156:157], 1, s[34:35]
	global_load_dwordx4 v[236:239], v[200:201], off offset:16
	global_load_dwordx4 v[240:243], v[200:201], off
	global_load_dwordx4 v[244:247], v[200:201], off offset:528
	global_load_dwordx4 v[150:153], v[200:201], off offset:512
	s_waitcnt vmcnt(14)
	v_pk_fma_f32 v[170:171], v[170:171], s[62:63], v[120:121] op_sel_hi:[1,0,1]
	v_pk_fma_f32 v[168:169], v[168:169], s[62:63], v[118:119] op_sel_hi:[1,0,1]
	v_pk_fma_f32 v[174:175], v[174:175], s[62:63], v[124:125] op_sel_hi:[1,0,1]
	v_pk_fma_f32 v[172:173], v[172:173], s[62:63], v[122:123] op_sel_hi:[1,0,1]
	s_nop 0
	v_cvt_pk_bf16_f32 v172, v172, v173
	v_cvt_pk_bf16_f32 v173, v174, v175
	v_cvt_pk_bf16_f32 v174, v168, v169
	v_cvt_pk_bf16_f32 v175, v170, v171
	global_store_dwordx4 v[134:135], v[172:175], off
	s_waitcnt vmcnt(13)
	v_pk_fma_f32 v[178:179], v[178:179], s[62:63], v[128:129] op_sel_hi:[1,0,1]
	v_pk_fma_f32 v[176:177], v[176:177], s[62:63], v[126:127] op_sel_hi:[1,0,1]
	v_pk_fma_f32 v[182:183], v[182:183], s[62:63], v[116:117] op_sel_hi:[1,0,1]
	v_pk_fma_f32 v[180:181], v[180:181], s[62:63], v[114:115] op_sel_hi:[1,0,1]
	s_nop 0
	v_cvt_pk_bf16_f32 v180, v180, v181
	v_cvt_pk_bf16_f32 v181, v182, v183
	v_cvt_pk_bf16_f32 v182, v176, v177
	v_cvt_pk_bf16_f32 v183, v178, v179
	global_store_dwordx4 v[134:135], v[180:183], off offset:256
	s_waitcnt vmcnt(12)
	v_pk_fma_f32 v[186:187], v[186:187], s[62:63], v[100:101] op_sel_hi:[1,0,1]
	v_pk_fma_f32 v[184:185], v[184:185], s[62:63], v[98:99] op_sel_hi:[1,0,1]
	v_pk_fma_f32 v[190:191], v[190:191], s[62:63], v[104:105] op_sel_hi:[1,0,1]
	v_pk_fma_f32 v[188:189], v[188:189], s[62:63], v[102:103] op_sel_hi:[1,0,1]
	s_nop 0
	v_cvt_pk_bf16_f32 v188, v188, v189
	v_cvt_pk_bf16_f32 v189, v190, v191
	v_cvt_pk_bf16_f32 v190, v184, v185
	v_cvt_pk_bf16_f32 v191, v186, v187
	global_store_dwordx4 v[136:137], v[188:191], off
	s_waitcnt vmcnt(11)
	v_pk_fma_f32 v[194:195], v[194:195], s[62:63], v[108:109] op_sel_hi:[1,0,1]
	v_pk_fma_f32 v[192:193], v[192:193], s[62:63], v[106:107] op_sel_hi:[1,0,1]
	v_pk_fma_f32 v[198:199], v[198:199], s[62:63], v[112:113] op_sel_hi:[1,0,1]
	v_pk_fma_f32 v[196:197], v[196:197], s[62:63], v[110:111] op_sel_hi:[1,0,1]
	s_nop 0
	v_cvt_pk_bf16_f32 v196, v196, v197
	v_cvt_pk_bf16_f32 v197, v198, v199
	v_cvt_pk_bf16_f32 v198, v192, v193
	v_cvt_pk_bf16_f32 v199, v194, v195
	global_store_dwordx4 v[136:137], v[196:199], off offset:256
	s_waitcnt vmcnt(10)
	v_pk_fma_f32 v[222:223], v[222:223], s[62:63], v[84:85] op_sel_hi:[1,0,1]
	v_pk_fma_f32 v[220:221], v[220:221], s[62:63], v[82:83] op_sel_hi:[1,0,1]
	v_pk_fma_f32 v[226:227], v[226:227], s[62:63], v[88:89] op_sel_hi:[1,0,1]
	v_pk_fma_f32 v[224:225], v[224:225], s[62:63], v[86:87] op_sel_hi:[1,0,1]
	s_nop 0
	v_cvt_pk_bf16_f32 v224, v224, v225
	v_cvt_pk_bf16_f32 v225, v226, v227
	v_cvt_pk_bf16_f32 v226, v220, v221
	v_cvt_pk_bf16_f32 v227, v222, v223
	global_store_dwordx4 v[154:155], v[224:227], off
	s_waitcnt vmcnt(9)
	v_pk_fma_f32 v[230:231], v[230:231], s[62:63], v[92:93] op_sel_hi:[1,0,1]
	v_pk_fma_f32 v[228:229], v[228:229], s[62:63], v[90:91] op_sel_hi:[1,0,1]
	v_pk_fma_f32 v[234:235], v[234:235], s[62:63], v[96:97] op_sel_hi:[1,0,1]
	v_pk_fma_f32 v[232:233], v[232:233], s[62:63], v[94:95] op_sel_hi:[1,0,1]
	s_nop 0
	v_cvt_pk_bf16_f32 v232, v232, v233
	v_cvt_pk_bf16_f32 v233, v234, v235
	v_cvt_pk_bf16_f32 v234, v228, v229
	v_cvt_pk_bf16_f32 v235, v230, v231
	global_store_dwordx4 v[154:155], v[232:235], off offset:256
	s_waitcnt vmcnt(8)
	v_pk_fma_f32 v[238:239], v[238:239], s[62:63], v[68:69] op_sel_hi:[1,0,1]
	v_pk_fma_f32 v[236:237], v[236:237], s[62:63], v[66:67] op_sel_hi:[1,0,1]
	v_pk_fma_f32 v[242:243], v[242:243], s[62:63], v[72:73] op_sel_hi:[1,0,1]
	v_pk_fma_f32 v[240:241], v[240:241], s[62:63], v[70:71] op_sel_hi:[1,0,1]
	s_nop 0
	v_cvt_pk_bf16_f32 v240, v240, v241
	v_cvt_pk_bf16_f32 v241, v242, v243
	v_cvt_pk_bf16_f32 v242, v236, v237
	v_cvt_pk_bf16_f32 v243, v238, v239
	global_store_dwordx4 v[156:157], v[240:243], off
	s_waitcnt vmcnt(7)
	v_pk_fma_f32 v[246:247], v[246:247], s[62:63], v[76:77] op_sel_hi:[1,0,1]
	v_pk_fma_f32 v[244:245], v[244:245], s[62:63], v[74:75] op_sel_hi:[1,0,1]
	v_pk_fma_f32 v[152:153], v[152:153], s[62:63], v[80:81] op_sel_hi:[1,0,1]
	v_pk_fma_f32 v[150:151], v[150:151], s[62:63], v[78:79] op_sel_hi:[1,0,1]
	s_nop 0
	v_cvt_pk_bf16_f32 v150, v150, v151
	v_cvt_pk_bf16_f32 v151, v152, v153
	v_cvt_pk_bf16_f32 v152, v244, v245
	v_cvt_pk_bf16_f32 v153, v246, v247
	global_store_dwordx4 v[156:157], v[150:153], off offset:256
	s_nop 1
	v_add_u32_e32 v133, 0x80, v132
	v_mad_i64_i32 v[134:135], s[24:25], s30, v133, v[130:131]
	v_lshl_add_u64 v[200:201], v[134:135], 2, s[94:95]
	v_lshl_add_u64 v[134:135], v[134:135], 1, s[34:35]
	global_load_dwordx4 v[168:171], v[200:201], off offset:16
	global_load_dwordx4 v[172:175], v[200:201], off
	global_load_dwordx4 v[176:179], v[200:201], off offset:528
	global_load_dwordx4 v[180:183], v[200:201], off offset:512
	v_add_u32_e32 v133, 0x90, v132
	v_mad_i64_i32 v[136:137], s[24:25], s30, v133, v[130:131]
	v_lshl_add_u64 v[200:201], v[136:137], 2, s[94:95]
	v_lshl_add_u64 v[136:137], v[136:137], 1, s[34:35]
	global_load_dwordx4 v[184:187], v[200:201], off offset:16
	global_load_dwordx4 v[188:191], v[200:201], off
	global_load_dwordx4 v[192:195], v[200:201], off offset:528
	global_load_dwordx4 v[196:199], v[200:201], off offset:512
	v_add_u32_e32 v133, 0xa0, v132
	v_mad_i64_i32 v[154:155], s[24:25], s30, v133, v[130:131]
	v_lshl_add_u64 v[200:201], v[154:155], 2, s[94:95]
	v_lshl_add_u64 v[154:155], v[154:155], 1, s[34:35]
	global_load_dwordx4 v[220:223], v[200:201], off offset:16
	global_load_dwordx4 v[224:227], v[200:201], off
	global_load_dwordx4 v[228:231], v[200:201], off offset:528
	global_load_dwordx4 v[232:235], v[200:201], off offset:512
	v_add_u32_e32 v133, 0xb0, v132
	v_mad_i64_i32 v[156:157], s[24:25], s30, v133, v[130:131]
	v_lshl_add_u64 v[200:201], v[156:157], 2, s[94:95]
	v_lshl_add_u64 v[156:157], v[156:157], 1, s[34:35]
	global_load_dwordx4 v[236:239], v[200:201], off offset:16
	global_load_dwordx4 v[240:243], v[200:201], off
	global_load_dwordx4 v[244:247], v[200:201], off offset:528
	global_load_dwordx4 v[150:153], v[200:201], off offset:512
	s_waitcnt vmcnt(14)
	v_pk_fma_f32 v[170:171], v[170:171], s[62:63], v[52:53] op_sel_hi:[1,0,1]
	v_pk_fma_f32 v[168:169], v[168:169], s[62:63], v[50:51] op_sel_hi:[1,0,1]
	v_pk_fma_f32 v[174:175], v[174:175], s[62:63], v[56:57] op_sel_hi:[1,0,1]
	v_pk_fma_f32 v[172:173], v[172:173], s[62:63], v[54:55] op_sel_hi:[1,0,1]
	s_nop 0
	v_cvt_pk_bf16_f32 v172, v172, v173
	v_cvt_pk_bf16_f32 v173, v174, v175
	v_cvt_pk_bf16_f32 v174, v168, v169
	v_cvt_pk_bf16_f32 v175, v170, v171
	global_store_dwordx4 v[134:135], v[172:175], off
	s_waitcnt vmcnt(13)
	v_pk_fma_f32 v[178:179], v[178:179], s[62:63], v[60:61] op_sel_hi:[1,0,1]
	v_pk_fma_f32 v[176:177], v[176:177], s[62:63], v[58:59] op_sel_hi:[1,0,1]
	v_pk_fma_f32 v[182:183], v[182:183], s[62:63], v[64:65] op_sel_hi:[1,0,1]
	v_pk_fma_f32 v[180:181], v[180:181], s[62:63], v[62:63] op_sel_hi:[1,0,1]
	s_nop 0
	v_cvt_pk_bf16_f32 v180, v180, v181
	v_cvt_pk_bf16_f32 v181, v182, v183
	v_cvt_pk_bf16_f32 v182, v176, v177
	v_cvt_pk_bf16_f32 v183, v178, v179
	global_store_dwordx4 v[134:135], v[180:183], off offset:256
	s_waitcnt vmcnt(12)
	v_pk_fma_f32 v[186:187], v[186:187], s[62:63], v[40:41] op_sel_hi:[1,0,1]
	v_pk_fma_f32 v[184:185], v[184:185], s[62:63], v[38:39] op_sel_hi:[1,0,1]
	v_pk_fma_f32 v[190:191], v[190:191], s[62:63], v[44:45] op_sel_hi:[1,0,1]
	v_pk_fma_f32 v[188:189], v[188:189], s[62:63], v[42:43] op_sel_hi:[1,0,1]
	s_nop 0
	v_cvt_pk_bf16_f32 v188, v188, v189
	v_cvt_pk_bf16_f32 v189, v190, v191
	v_cvt_pk_bf16_f32 v190, v184, v185
	v_cvt_pk_bf16_f32 v191, v186, v187
	global_store_dwordx4 v[136:137], v[188:191], off
	s_waitcnt vmcnt(11)
	v_pk_fma_f32 v[194:195], v[194:195], s[62:63], v[36:37] op_sel_hi:[1,0,1]
	v_pk_fma_f32 v[192:193], v[192:193], s[62:63], v[34:35] op_sel_hi:[1,0,1]
	v_pk_fma_f32 v[198:199], v[198:199], s[62:63], v[48:49] op_sel_hi:[1,0,1]
	v_pk_fma_f32 v[196:197], v[196:197], s[62:63], v[46:47] op_sel_hi:[1,0,1]
	s_nop 0
	v_cvt_pk_bf16_f32 v196, v196, v197
	v_cvt_pk_bf16_f32 v197, v198, v199
	v_cvt_pk_bf16_f32 v198, v192, v193
	v_cvt_pk_bf16_f32 v199, v194, v195
	global_store_dwordx4 v[136:137], v[196:199], off offset:256
	s_waitcnt vmcnt(10)
	v_pk_fma_f32 v[222:223], v[222:223], s[62:63], v[28:29] op_sel_hi:[1,0,1]
	v_pk_fma_f32 v[220:221], v[220:221], s[62:63], v[26:27] op_sel_hi:[1,0,1]
	v_pk_fma_f32 v[226:227], v[226:227], s[62:63], v[32:33] op_sel_hi:[1,0,1]
	v_pk_fma_f32 v[224:225], v[224:225], s[62:63], v[30:31] op_sel_hi:[1,0,1]
	s_nop 0
	v_cvt_pk_bf16_f32 v224, v224, v225
	v_cvt_pk_bf16_f32 v225, v226, v227
	v_cvt_pk_bf16_f32 v226, v220, v221
	v_cvt_pk_bf16_f32 v227, v222, v223
	global_store_dwordx4 v[154:155], v[224:227], off
	s_waitcnt vmcnt(9)
	v_pk_fma_f32 v[230:231], v[230:231], s[62:63], v[20:21] op_sel_hi:[1,0,1]
	v_pk_fma_f32 v[228:229], v[228:229], s[62:63], v[18:19] op_sel_hi:[1,0,1]
	v_pk_fma_f32 v[234:235], v[234:235], s[62:63], v[24:25] op_sel_hi:[1,0,1]
	v_pk_fma_f32 v[232:233], v[232:233], s[62:63], v[22:23] op_sel_hi:[1,0,1]
	s_nop 0
	v_cvt_pk_bf16_f32 v232, v232, v233
	v_cvt_pk_bf16_f32 v233, v234, v235
	v_cvt_pk_bf16_f32 v234, v228, v229
	v_cvt_pk_bf16_f32 v235, v230, v231
	global_store_dwordx4 v[154:155], v[232:235], off offset:256
	s_waitcnt vmcnt(8)
	v_pk_fma_f32 v[238:239], v[238:239], s[62:63], v[12:13] op_sel_hi:[1,0,1]
	v_pk_fma_f32 v[236:237], v[236:237], s[62:63], v[10:11] op_sel_hi:[1,0,1]
	v_pk_fma_f32 v[242:243], v[242:243], s[62:63], v[16:17] op_sel_hi:[1,0,1]
	v_pk_fma_f32 v[240:241], v[240:241], s[62:63], v[14:15] op_sel_hi:[1,0,1]
	s_nop 0
	v_cvt_pk_bf16_f32 v240, v240, v241
	v_cvt_pk_bf16_f32 v241, v242, v243
	v_cvt_pk_bf16_f32 v242, v236, v237
	v_cvt_pk_bf16_f32 v243, v238, v239
	global_store_dwordx4 v[156:157], v[240:243], off
	s_waitcnt vmcnt(7)
	v_pk_fma_f32 v[246:247], v[246:247], s[62:63], v[4:5] op_sel_hi:[1,0,1]
	v_pk_fma_f32 v[244:245], v[244:245], s[62:63], v[2:3] op_sel_hi:[1,0,1]
	v_pk_fma_f32 v[152:153], v[152:153], s[62:63], v[8:9] op_sel_hi:[1,0,1]
	v_pk_fma_f32 v[150:151], v[150:151], s[62:63], v[6:7] op_sel_hi:[1,0,1]
	s_nop 0
	v_cvt_pk_bf16_f32 v150, v150, v151
	v_cvt_pk_bf16_f32 v151, v152, v153
	v_cvt_pk_bf16_f32 v152, v244, v245
	v_cvt_pk_bf16_f32 v153, v246, v247
	global_store_dwordx4 v[156:157], v[150:153], off offset:256
	s_nop 1
